# attention epilogues: gate loads (each value read once) marked nt
# speedup vs baseline: 1.0019x; 1.0019x over previous
; DI unsigned pk2(float a, float b) { f32x2 v = {a, b}; bf16v2 r = __builtin_convertvector(v, bf16v2); return __builtin_bit_cast(unsigned, r); }
; DI float bf_lo(unsigned u) { return __uint_as_float(u << 16); }
; DI float bf_hi(unsigned u) { return __uint_as_float(u & 0xffff0000u); }
; DI size_t zrowU(int row0, int NT) { return ((size_t)((row0 >> 8) * NT) << 16) + (size_t)((((row0 >> 7) & 1) << 15) | (((row0 >> 5) & 1) << 14) | (((row0 >> 6) & 1) << 11)); }
; DI unsigned zlaneRC(int r5, int col) { return (unsigned)(((col >> 8) << 16) | ((r5 >> 4) << 13) | (((col >> 7) & 1) << 12) | (((col >> 5) & 3) << 9) | (((col >> 3) & 3) << 7) | ((r5 & 15) << 3) | (col & 7)); }
; DI float silu_mul(float o, float g) { return o * g * __builtin_amdgcn_rcpf(1.0f + __builtin_amdgcn_exp2f(g * -1.4426950408889634f)); }
; DI void attnB_item(bf16_t* z, int hh, int qs, LAS bf16_t* vs, int lane) {
;     ...
;     if (!metaq || c < NMETA) {
;         bf16_t* orow = z + zrowU(qrow0, 32) + zlaneRC(c, hh * 128 + 4 * h);
;         const bf16_t* grow = z + zrowU(qrow0, 32) + zlaneRC(c, 6144 + hh * 128 + 4 * h);
; #pragma unroll
;         for (int dt = 0; dt < 4; ++dt)
; #pragma unroll
;             for (int g = 0; g < 4; ++g) {
;                 const int d0 = (dt << 9) | (g << 7);
;                 const u32x2 gv = *(const u32x2*)(grow + d0);
;                 u32x2 o; o.x = pk2(silu_mul(acc[dt][4 * g], bf_lo(gv.x)), silu_mul(acc[dt][4 * g + 1], bf_hi(gv.x)));
;                 o.y = pk2(silu_mul(acc[dt][4 * g + 2], bf_lo(gv.y)), silu_mul(acc[dt][4 * g + 3], bf_hi(gv.y)));
;                 *(u32x2*)(orow + d0) = o;
;             }
; DI bool attn_next(AttnQueue& q, int lane0, int& qs, int& hd) {
;     ...
;         if (lane0) n = __hip_atomic_fetch_add(q.heads + 64 * xq, 1u, __ATOMIC_RELAXED, __HIP_MEMORY_SCOPE_AGENT);
.LBB0_157:
	v_cmp_gt_u32_e32 vcc, 16, v178
	s_or_b64 s[0:1], s[0:1], vcc
	s_and_saveexec_b64 s[4:5], s[0:1]
	s_xor_b64 s[0:1], exec, s[4:5]
	s_cbranch_execz .LBB0_130
	v_add_u32_e32 v0, s27, v183
	v_lshlrev_b32_e32 v66, 8, v0
	v_lshlrev_b32_e32 v0, 5, v0
	v_lshlrev_b32_e32 v67, 6, v180
	v_and_b32_e32 v0, 0x1000, v0
	v_and_b32_e32 v68, 0x780, v67
	v_and_b32_e32 v69, 4, v183
	v_or_b32_e32 v67, v68, v69
	v_and_or_b32 v70, v66, s12, v0
	v_or3_b32 v0, v67, v181, v70
	v_lshl_add_u64 v[146:147], v[0:1], 1, s[46:47]
	v_or3_b32 v0, v70, v69, v68
	s_mov_b32 s4, 0x180000
	v_add3_u32 v0, v0, v181, s4
	v_lshl_add_u64 v[148:149], v[0:1], 1, s[46:47]
	global_load_dwordx2 v[192:193], v[148:149], off nt
	global_load_dwordx2 v[194:195], v[148:149], off offset:256 nt
	global_load_dwordx2 v[196:197], v[148:149], off offset:512 nt
	global_load_dwordx2 v[198:199], v[148:149], off offset:768 nt
	global_load_dwordx2 v[200:201], v[148:149], off offset:1024 nt
	global_load_dwordx2 v[202:203], v[148:149], off offset:1280 nt
	global_load_dwordx2 v[204:205], v[148:149], off offset:1536 nt
	global_load_dwordx2 v[206:207], v[148:149], off offset:1792 nt
	global_load_dwordx2 v[208:209], v[148:149], off offset:2048 nt
	global_load_dwordx2 v[210:211], v[148:149], off offset:2304 nt
	global_load_dwordx2 v[212:213], v[148:149], off offset:2560 nt
	global_load_dwordx2 v[214:215], v[148:149], off offset:2816 nt
	global_load_dwordx2 v[216:217], v[148:149], off offset:3072 nt
	global_load_dwordx2 v[218:219], v[148:149], off offset:3328 nt
	global_load_dwordx2 v[220:221], v[148:149], off offset:3584 nt
	global_load_dwordx2 v[222:223], v[148:149], off offset:3840 nt
	s_add_i32 s5, s26, s33
	s_and_b32 s5, s5, 7
	s_lshl_b32 s5, s5, 8
	s_mov_b64 vcc, exec
	s_mov_b64 exec, 1
	v_mov_b32_e32 v66, s5
	v_mov_b32_e32 v67, 1
	global_atomic_add v240, v66, v67, s[34:35] sc0
	s_mov_b64 exec, vcc
	s_mov_b32 s100, 1
	s_waitcnt vmcnt(16)
	v_lshlrev_b32_e32 v66, 16, v192
	v_and_b32_e32 v67, 0xffff0000, v192
	v_lshlrev_b32_e32 v68, 16, v193
	v_and_b32_e32 v69, 0xffff0000, v193
	v_mul_f32_e32 v70, 0xbfb8aa3b, v66
	v_mul_f32_e32 v71, 0xbfb8aa3b, v67
	v_mul_f32_e32 v72, 0xbfb8aa3b, v68
	v_mul_f32_e32 v73, 0xbfb8aa3b, v69
	v_exp_f32_e32 v70, v70
	v_exp_f32_e32 v71, v71
	v_exp_f32_e32 v72, v72
	v_exp_f32_e32 v73, v73
	v_pk_mul_f32 v[50:51], v[50:51], v[66:67]
	v_pk_mul_f32 v[52:53], v[52:53], v[68:69]
	v_add_f32_e32 v70, 1.0, v70
	v_add_f32_e32 v71, 1.0, v71
	v_add_f32_e32 v72, 1.0, v72
	v_add_f32_e32 v73, 1.0, v73
	v_rcp_f32_e32 v70, v70
	v_rcp_f32_e32 v71, v71
	v_rcp_f32_e32 v72, v72
	v_rcp_f32_e32 v73, v73
	v_pk_mul_f32 v[50:51], v[50:51], v[70:71]
	v_pk_mul_f32 v[52:53], v[52:53], v[72:73]
	v_cvt_pk_bf16_f32 v50, v50, v51
	v_cvt_pk_bf16_f32 v51, v52, v53
	s_waitcnt vmcnt(15)
	v_lshlrev_b32_e32 v74, 16, v194
	v_and_b32_e32 v75, 0xffff0000, v194
	v_lshlrev_b32_e32 v76, 16, v195
	v_and_b32_e32 v77, 0xffff0000, v195
	v_mul_f32_e32 v78, 0xbfb8aa3b, v74
	v_mul_f32_e32 v79, 0xbfb8aa3b, v75
	v_mul_f32_e32 v80, 0xbfb8aa3b, v76
	v_mul_f32_e32 v81, 0xbfb8aa3b, v77
	v_exp_f32_e32 v78, v78
	v_exp_f32_e32 v79, v79
	v_exp_f32_e32 v80, v80
	v_exp_f32_e32 v81, v81
	v_pk_mul_f32 v[54:55], v[54:55], v[74:75]
	v_pk_mul_f32 v[56:57], v[56:57], v[76:77]
	v_add_f32_e32 v78, 1.0, v78
	v_add_f32_e32 v79, 1.0, v79
	v_add_f32_e32 v80, 1.0, v80
	v_add_f32_e32 v81, 1.0, v81
	v_rcp_f32_e32 v78, v78
	v_rcp_f32_e32 v79, v79
	v_rcp_f32_e32 v80, v80
	v_rcp_f32_e32 v81, v81
	v_pk_mul_f32 v[54:55], v[54:55], v[78:79]
	v_pk_mul_f32 v[56:57], v[56:57], v[80:81]
	v_cvt_pk_bf16_f32 v54, v54, v55
	v_cvt_pk_bf16_f32 v55, v56, v57
	s_waitcnt vmcnt(14)
	v_lshlrev_b32_e32 v66, 16, v196
	v_and_b32_e32 v67, 0xffff0000, v196
	v_lshlrev_b32_e32 v68, 16, v197
	v_and_b32_e32 v69, 0xffff0000, v197
	v_mul_f32_e32 v70, 0xbfb8aa3b, v66
	v_mul_f32_e32 v71, 0xbfb8aa3b, v67
	v_mul_f32_e32 v72, 0xbfb8aa3b, v68
	v_mul_f32_e32 v73, 0xbfb8aa3b, v69
	v_exp_f32_e32 v70, v70
	v_exp_f32_e32 v71, v71
	v_exp_f32_e32 v72, v72
	v_exp_f32_e32 v73, v73
	v_pk_mul_f32 v[58:59], v[58:59], v[66:67]
	v_pk_mul_f32 v[60:61], v[60:61], v[68:69]
	v_add_f32_e32 v70, 1.0, v70
	v_add_f32_e32 v71, 1.0, v71
	v_add_f32_e32 v72, 1.0, v72
	v_add_f32_e32 v73, 1.0, v73
	v_rcp_f32_e32 v70, v70
	v_rcp_f32_e32 v71, v71
	v_rcp_f32_e32 v72, v72
	v_rcp_f32_e32 v73, v73
	v_pk_mul_f32 v[58:59], v[58:59], v[70:71]
	v_pk_mul_f32 v[60:61], v[60:61], v[72:73]
	v_cvt_pk_bf16_f32 v58, v58, v59
	v_cvt_pk_bf16_f32 v59, v60, v61
	s_waitcnt vmcnt(13)
	v_lshlrev_b32_e32 v74, 16, v198
	v_and_b32_e32 v75, 0xffff0000, v198
	v_lshlrev_b32_e32 v76, 16, v199
	v_and_b32_e32 v77, 0xffff0000, v199
	v_mul_f32_e32 v78, 0xbfb8aa3b, v74
	v_mul_f32_e32 v79, 0xbfb8aa3b, v75
	v_mul_f32_e32 v80, 0xbfb8aa3b, v76
	v_mul_f32_e32 v81, 0xbfb8aa3b, v77
	v_exp_f32_e32 v78, v78
	v_exp_f32_e32 v79, v79
	v_exp_f32_e32 v80, v80
	v_exp_f32_e32 v81, v81
	v_pk_mul_f32 v[62:63], v[62:63], v[74:75]
	v_pk_mul_f32 v[64:65], v[64:65], v[76:77]
	v_add_f32_e32 v78, 1.0, v78
	v_add_f32_e32 v79, 1.0, v79
	v_add_f32_e32 v80, 1.0, v80
	v_add_f32_e32 v81, 1.0, v81
	v_rcp_f32_e32 v78, v78
	v_rcp_f32_e32 v79, v79
	v_rcp_f32_e32 v80, v80
	v_rcp_f32_e32 v81, v81
	v_pk_mul_f32 v[62:63], v[62:63], v[78:79]
	v_pk_mul_f32 v[64:65], v[64:65], v[80:81]
	v_cvt_pk_bf16_f32 v62, v62, v63
	v_cvt_pk_bf16_f32 v63, v64, v65
	s_waitcnt vmcnt(12)
; DI unsigned pk2(float a, float b) { f32x2 v = {a, b}; bf16v2 r = __builtin_convertvector(v, bf16v2); return __builtin_bit_cast(unsigned, r); }
; DI float bf_lo(unsigned u) { return __uint_as_float(u << 16); }
; DI float bf_hi(unsigned u) { return __uint_as_float(u & 0xffff0000u); }
; DI float silu_mul(float o, float g) { return o * g * __builtin_amdgcn_rcpf(1.0f + __builtin_amdgcn_exp2f(g * -1.4426950408889634f)); }
; DI void attnB_item(bf16_t* z, int hh, int qs, LAS bf16_t* vs, int lane) {
;     ...
;             for (int g = 0; g < 4; ++g) {
;                 const int d0 = (dt << 9) | (g << 7);
;                 const u32x2 gv = *(const u32x2*)(grow + d0);
;                 u32x2 o; o.x = pk2(silu_mul(acc[dt][4 * g], bf_lo(gv.x)), silu_mul(acc[dt][4 * g + 1], bf_hi(gv.x)));
;                 o.y = pk2(silu_mul(acc[dt][4 * g + 2], bf_lo(gv.y)), silu_mul(acc[dt][4 * g + 3], bf_hi(gv.y)));
;                 *(u32x2*)(orow + d0) = o;
	v_lshlrev_b32_e32 v66, 16, v200
	v_and_b32_e32 v67, 0xffff0000, v200
	v_lshlrev_b32_e32 v68, 16, v201
	v_and_b32_e32 v69, 0xffff0000, v201
	v_mul_f32_e32 v70, 0xbfb8aa3b, v66
	v_mul_f32_e32 v71, 0xbfb8aa3b, v67
	v_mul_f32_e32 v72, 0xbfb8aa3b, v68
	v_mul_f32_e32 v73, 0xbfb8aa3b, v69
	v_exp_f32_e32 v70, v70
	v_exp_f32_e32 v71, v71
	v_exp_f32_e32 v72, v72
	v_exp_f32_e32 v73, v73
	v_pk_mul_f32 v[34:35], v[34:35], v[66:67]
	v_pk_mul_f32 v[36:37], v[36:37], v[68:69]
	v_add_f32_e32 v70, 1.0, v70
	v_add_f32_e32 v71, 1.0, v71
	v_add_f32_e32 v72, 1.0, v72
	v_add_f32_e32 v73, 1.0, v73
	v_rcp_f32_e32 v70, v70
	v_rcp_f32_e32 v71, v71
	v_rcp_f32_e32 v72, v72
	v_rcp_f32_e32 v73, v73
	v_pk_mul_f32 v[34:35], v[34:35], v[70:71]
	v_pk_mul_f32 v[36:37], v[36:37], v[72:73]
	v_cvt_pk_bf16_f32 v34, v34, v35
	v_cvt_pk_bf16_f32 v35, v36, v37
	s_waitcnt vmcnt(11)
	v_lshlrev_b32_e32 v74, 16, v202
	v_and_b32_e32 v75, 0xffff0000, v202
	v_lshlrev_b32_e32 v76, 16, v203
	v_and_b32_e32 v77, 0xffff0000, v203
	v_mul_f32_e32 v78, 0xbfb8aa3b, v74
	v_mul_f32_e32 v79, 0xbfb8aa3b, v75
	v_mul_f32_e32 v80, 0xbfb8aa3b, v76
	v_mul_f32_e32 v81, 0xbfb8aa3b, v77
	v_exp_f32_e32 v78, v78
	v_exp_f32_e32 v79, v79
	v_exp_f32_e32 v80, v80
	v_exp_f32_e32 v81, v81
	v_pk_mul_f32 v[38:39], v[38:39], v[74:75]
	v_pk_mul_f32 v[40:41], v[40:41], v[76:77]
	v_add_f32_e32 v78, 1.0, v78
	v_add_f32_e32 v79, 1.0, v79
	v_add_f32_e32 v80, 1.0, v80
	v_add_f32_e32 v81, 1.0, v81
	v_rcp_f32_e32 v78, v78
	v_rcp_f32_e32 v79, v79
	v_rcp_f32_e32 v80, v80
	v_rcp_f32_e32 v81, v81
	v_pk_mul_f32 v[38:39], v[38:39], v[78:79]
	v_pk_mul_f32 v[40:41], v[40:41], v[80:81]
	v_cvt_pk_bf16_f32 v38, v38, v39
	v_cvt_pk_bf16_f32 v39, v40, v41
	s_waitcnt vmcnt(10)
	v_lshlrev_b32_e32 v66, 16, v204
	v_and_b32_e32 v67, 0xffff0000, v204
	v_lshlrev_b32_e32 v68, 16, v205
	v_and_b32_e32 v69, 0xffff0000, v205
	v_mul_f32_e32 v70, 0xbfb8aa3b, v66
	v_mul_f32_e32 v71, 0xbfb8aa3b, v67
	v_mul_f32_e32 v72, 0xbfb8aa3b, v68
	v_mul_f32_e32 v73, 0xbfb8aa3b, v69
	v_exp_f32_e32 v70, v70
	v_exp_f32_e32 v71, v71
	v_exp_f32_e32 v72, v72
	v_exp_f32_e32 v73, v73
	v_pk_mul_f32 v[42:43], v[42:43], v[66:67]
	v_pk_mul_f32 v[44:45], v[44:45], v[68:69]
	v_add_f32_e32 v70, 1.0, v70
	v_add_f32_e32 v71, 1.0, v71
	v_add_f32_e32 v72, 1.0, v72
	v_add_f32_e32 v73, 1.0, v73
	v_rcp_f32_e32 v70, v70
	v_rcp_f32_e32 v71, v71
	v_rcp_f32_e32 v72, v72
	v_rcp_f32_e32 v73, v73
	v_pk_mul_f32 v[42:43], v[42:43], v[70:71]
	v_pk_mul_f32 v[44:45], v[44:45], v[72:73]
	v_cvt_pk_bf16_f32 v42, v42, v43
	v_cvt_pk_bf16_f32 v43, v44, v45
	s_waitcnt vmcnt(9)
	v_lshlrev_b32_e32 v74, 16, v206
	v_and_b32_e32 v75, 0xffff0000, v206
	v_lshlrev_b32_e32 v76, 16, v207
	v_and_b32_e32 v77, 0xffff0000, v207
	v_mul_f32_e32 v78, 0xbfb8aa3b, v74
	v_mul_f32_e32 v79, 0xbfb8aa3b, v75
	v_mul_f32_e32 v80, 0xbfb8aa3b, v76
	v_mul_f32_e32 v81, 0xbfb8aa3b, v77
	v_exp_f32_e32 v78, v78
	v_exp_f32_e32 v79, v79
	v_exp_f32_e32 v80, v80
	v_exp_f32_e32 v81, v81
	v_pk_mul_f32 v[46:47], v[46:47], v[74:75]
	v_pk_mul_f32 v[48:49], v[48:49], v[76:77]
	v_add_f32_e32 v78, 1.0, v78
	v_add_f32_e32 v79, 1.0, v79
	v_add_f32_e32 v80, 1.0, v80
	v_add_f32_e32 v81, 1.0, v81
	v_rcp_f32_e32 v78, v78
	v_rcp_f32_e32 v79, v79
	v_rcp_f32_e32 v80, v80
	v_rcp_f32_e32 v81, v81
	v_pk_mul_f32 v[46:47], v[46:47], v[78:79]
	v_pk_mul_f32 v[48:49], v[48:49], v[80:81]
	v_cvt_pk_bf16_f32 v46, v46, v47
	v_cvt_pk_bf16_f32 v47, v48, v49
	s_waitcnt vmcnt(8)
	v_lshlrev_b32_e32 v66, 16, v208
	v_and_b32_e32 v67, 0xffff0000, v208
	v_lshlrev_b32_e32 v68, 16, v209
	v_and_b32_e32 v69, 0xffff0000, v209
	v_mul_f32_e32 v70, 0xbfb8aa3b, v66
	v_mul_f32_e32 v71, 0xbfb8aa3b, v67
	v_mul_f32_e32 v72, 0xbfb8aa3b, v68
	v_mul_f32_e32 v73, 0xbfb8aa3b, v69
	v_exp_f32_e32 v70, v70
	v_exp_f32_e32 v71, v71
	v_exp_f32_e32 v72, v72
	v_exp_f32_e32 v73, v73
	v_pk_mul_f32 v[18:19], v[18:19], v[66:67]
	v_pk_mul_f32 v[20:21], v[20:21], v[68:69]
	v_add_f32_e32 v70, 1.0, v70
	v_add_f32_e32 v71, 1.0, v71
	v_add_f32_e32 v72, 1.0, v72
	v_add_f32_e32 v73, 1.0, v73
	v_rcp_f32_e32 v70, v70
	v_rcp_f32_e32 v71, v71
	v_rcp_f32_e32 v72, v72
	v_rcp_f32_e32 v73, v73
	v_pk_mul_f32 v[18:19], v[18:19], v[70:71]
	v_pk_mul_f32 v[20:21], v[20:21], v[72:73]
	v_cvt_pk_bf16_f32 v18, v18, v19
	v_cvt_pk_bf16_f32 v19, v20, v21
	s_waitcnt vmcnt(7)
	v_lshlrev_b32_e32 v74, 16, v210
	v_and_b32_e32 v75, 0xffff0000, v210
	v_lshlrev_b32_e32 v76, 16, v211
	v_and_b32_e32 v77, 0xffff0000, v211
	v_mul_f32_e32 v78, 0xbfb8aa3b, v74
	v_mul_f32_e32 v79, 0xbfb8aa3b, v75
	v_mul_f32_e32 v80, 0xbfb8aa3b, v76
	v_mul_f32_e32 v81, 0xbfb8aa3b, v77
	v_exp_f32_e32 v78, v78
	v_exp_f32_e32 v79, v79
	v_exp_f32_e32 v80, v80
	v_exp_f32_e32 v81, v81
	v_pk_mul_f32 v[22:23], v[22:23], v[74:75]
	v_pk_mul_f32 v[24:25], v[24:25], v[76:77]
	v_add_f32_e32 v78, 1.0, v78
	v_add_f32_e32 v79, 1.0, v79
	v_add_f32_e32 v80, 1.0, v80
	v_add_f32_e32 v81, 1.0, v81
	v_rcp_f32_e32 v78, v78
	v_rcp_f32_e32 v79, v79
	v_rcp_f32_e32 v80, v80
	v_rcp_f32_e32 v81, v81
	v_pk_mul_f32 v[22:23], v[22:23], v[78:79]
	v_pk_mul_f32 v[24:25], v[24:25], v[80:81]
	v_cvt_pk_bf16_f32 v22, v22, v23
	v_cvt_pk_bf16_f32 v23, v24, v25
	s_waitcnt vmcnt(6)
	v_lshlrev_b32_e32 v66, 16, v212
	v_and_b32_e32 v67, 0xffff0000, v212
	v_lshlrev_b32_e32 v68, 16, v213
	v_and_b32_e32 v69, 0xffff0000, v213
	v_mul_f32_e32 v70, 0xbfb8aa3b, v66
	v_mul_f32_e32 v71, 0xbfb8aa3b, v67
	v_mul_f32_e32 v72, 0xbfb8aa3b, v68
	v_mul_f32_e32 v73, 0xbfb8aa3b, v69
	v_exp_f32_e32 v70, v70
	v_exp_f32_e32 v71, v71
	v_exp_f32_e32 v72, v72
	v_exp_f32_e32 v73, v73
	v_pk_mul_f32 v[26:27], v[26:27], v[66:67]
	v_pk_mul_f32 v[28:29], v[28:29], v[68:69]
	v_add_f32_e32 v70, 1.0, v70
	v_add_f32_e32 v71, 1.0, v71
	v_add_f32_e32 v72, 1.0, v72
	v_add_f32_e32 v73, 1.0, v73
	v_rcp_f32_e32 v70, v70
	v_rcp_f32_e32 v71, v71
	v_rcp_f32_e32 v72, v72
	v_rcp_f32_e32 v73, v73
	v_pk_mul_f32 v[26:27], v[26:27], v[70:71]
	v_pk_mul_f32 v[28:29], v[28:29], v[72:73]
	v_cvt_pk_bf16_f32 v26, v26, v27
	v_cvt_pk_bf16_f32 v27, v28, v29
	s_waitcnt vmcnt(5)
; DI unsigned pk2(float a, float b) { f32x2 v = {a, b}; bf16v2 r = __builtin_convertvector(v, bf16v2); return __builtin_bit_cast(unsigned, r); }
; DI float bf_lo(unsigned u) { return __uint_as_float(u << 16); }
; DI float bf_hi(unsigned u) { return __uint_as_float(u & 0xffff0000u); }
; DI float silu_mul(float o, float g) { return o * g * __builtin_amdgcn_rcpf(1.0f + __builtin_amdgcn_exp2f(g * -1.4426950408889634f)); }
; DI void attnB_item(bf16_t* z, int hh, int qs, LAS bf16_t* vs, int lane) {
;     ...
;             for (int g = 0; g < 4; ++g) {
;                 const int d0 = (dt << 9) | (g << 7);
;                 const u32x2 gv = *(const u32x2*)(grow + d0);
;                 u32x2 o; o.x = pk2(silu_mul(acc[dt][4 * g], bf_lo(gv.x)), silu_mul(acc[dt][4 * g + 1], bf_hi(gv.x)));
;                 o.y = pk2(silu_mul(acc[dt][4 * g + 2], bf_lo(gv.y)), silu_mul(acc[dt][4 * g + 3], bf_hi(gv.y)));
;                 *(u32x2*)(orow + d0) = o;
;             }
	v_lshlrev_b32_e32 v74, 16, v214
	v_and_b32_e32 v75, 0xffff0000, v214
	v_lshlrev_b32_e32 v76, 16, v215
	v_and_b32_e32 v77, 0xffff0000, v215
	v_mul_f32_e32 v78, 0xbfb8aa3b, v74
	v_mul_f32_e32 v79, 0xbfb8aa3b, v75
	v_mul_f32_e32 v80, 0xbfb8aa3b, v76
	v_mul_f32_e32 v81, 0xbfb8aa3b, v77
	v_exp_f32_e32 v78, v78
	v_exp_f32_e32 v79, v79
	v_exp_f32_e32 v80, v80
	v_exp_f32_e32 v81, v81
	v_pk_mul_f32 v[30:31], v[30:31], v[74:75]
	v_pk_mul_f32 v[32:33], v[32:33], v[76:77]
	v_add_f32_e32 v78, 1.0, v78
	v_add_f32_e32 v79, 1.0, v79
	v_add_f32_e32 v80, 1.0, v80
	v_add_f32_e32 v81, 1.0, v81
	v_rcp_f32_e32 v78, v78
	v_rcp_f32_e32 v79, v79
	v_rcp_f32_e32 v80, v80
	v_rcp_f32_e32 v81, v81
	v_pk_mul_f32 v[30:31], v[30:31], v[78:79]
	v_pk_mul_f32 v[32:33], v[32:33], v[80:81]
	v_cvt_pk_bf16_f32 v30, v30, v31
	v_cvt_pk_bf16_f32 v31, v32, v33
	s_waitcnt vmcnt(4)
	v_lshlrev_b32_e32 v66, 16, v216
	v_and_b32_e32 v67, 0xffff0000, v216
	v_lshlrev_b32_e32 v68, 16, v217
	v_and_b32_e32 v69, 0xffff0000, v217
	v_mul_f32_e32 v70, 0xbfb8aa3b, v66
	v_mul_f32_e32 v71, 0xbfb8aa3b, v67
	v_mul_f32_e32 v72, 0xbfb8aa3b, v68
	v_mul_f32_e32 v73, 0xbfb8aa3b, v69
	v_exp_f32_e32 v70, v70
	v_exp_f32_e32 v71, v71
	v_exp_f32_e32 v72, v72
	v_exp_f32_e32 v73, v73
	v_pk_mul_f32 v[2:3], v[2:3], v[66:67]
	v_pk_mul_f32 v[4:5], v[4:5], v[68:69]
	v_add_f32_e32 v70, 1.0, v70
	v_add_f32_e32 v71, 1.0, v71
	v_add_f32_e32 v72, 1.0, v72
	v_add_f32_e32 v73, 1.0, v73
	v_rcp_f32_e32 v70, v70
	v_rcp_f32_e32 v71, v71
	v_rcp_f32_e32 v72, v72
	v_rcp_f32_e32 v73, v73
	v_pk_mul_f32 v[2:3], v[2:3], v[70:71]
	v_pk_mul_f32 v[4:5], v[4:5], v[72:73]
	v_cvt_pk_bf16_f32 v2, v2, v3
	v_cvt_pk_bf16_f32 v3, v4, v5
	s_waitcnt vmcnt(3)
	v_lshlrev_b32_e32 v74, 16, v218
	v_and_b32_e32 v75, 0xffff0000, v218
	v_lshlrev_b32_e32 v76, 16, v219
	v_and_b32_e32 v77, 0xffff0000, v219
	v_mul_f32_e32 v78, 0xbfb8aa3b, v74
	v_mul_f32_e32 v79, 0xbfb8aa3b, v75
	v_mul_f32_e32 v80, 0xbfb8aa3b, v76
	v_mul_f32_e32 v81, 0xbfb8aa3b, v77
	v_exp_f32_e32 v78, v78
	v_exp_f32_e32 v79, v79
	v_exp_f32_e32 v80, v80
	v_exp_f32_e32 v81, v81
	v_pk_mul_f32 v[6:7], v[6:7], v[74:75]
	v_pk_mul_f32 v[8:9], v[8:9], v[76:77]
	v_add_f32_e32 v78, 1.0, v78
	v_add_f32_e32 v79, 1.0, v79
	v_add_f32_e32 v80, 1.0, v80
	v_add_f32_e32 v81, 1.0, v81
	v_rcp_f32_e32 v78, v78
	v_rcp_f32_e32 v79, v79
	v_rcp_f32_e32 v80, v80
	v_rcp_f32_e32 v81, v81
	v_pk_mul_f32 v[6:7], v[6:7], v[78:79]
	v_pk_mul_f32 v[8:9], v[8:9], v[80:81]
	v_cvt_pk_bf16_f32 v6, v6, v7
	v_cvt_pk_bf16_f32 v7, v8, v9
	s_waitcnt vmcnt(2)
	v_lshlrev_b32_e32 v66, 16, v220
	v_and_b32_e32 v67, 0xffff0000, v220
	v_lshlrev_b32_e32 v68, 16, v221
	v_and_b32_e32 v69, 0xffff0000, v221
	v_mul_f32_e32 v70, 0xbfb8aa3b, v66
	v_mul_f32_e32 v71, 0xbfb8aa3b, v67
	v_mul_f32_e32 v72, 0xbfb8aa3b, v68
	v_mul_f32_e32 v73, 0xbfb8aa3b, v69
	v_exp_f32_e32 v70, v70
	v_exp_f32_e32 v71, v71
	v_exp_f32_e32 v72, v72
	v_exp_f32_e32 v73, v73
	v_pk_mul_f32 v[10:11], v[10:11], v[66:67]
	v_pk_mul_f32 v[12:13], v[12:13], v[68:69]
	v_add_f32_e32 v70, 1.0, v70
	v_add_f32_e32 v71, 1.0, v71
	v_add_f32_e32 v72, 1.0, v72
	v_add_f32_e32 v73, 1.0, v73
	v_rcp_f32_e32 v70, v70
	v_rcp_f32_e32 v71, v71
	v_rcp_f32_e32 v72, v72
	v_rcp_f32_e32 v73, v73
	v_pk_mul_f32 v[10:11], v[10:11], v[70:71]
	v_pk_mul_f32 v[12:13], v[12:13], v[72:73]
	v_cvt_pk_bf16_f32 v10, v10, v11
	v_cvt_pk_bf16_f32 v11, v12, v13
	s_waitcnt vmcnt(1)
	v_lshlrev_b32_e32 v74, 16, v222
	v_and_b32_e32 v75, 0xffff0000, v222
	v_lshlrev_b32_e32 v76, 16, v223
	v_and_b32_e32 v77, 0xffff0000, v223
	v_mul_f32_e32 v78, 0xbfb8aa3b, v74
	v_mul_f32_e32 v79, 0xbfb8aa3b, v75
	v_mul_f32_e32 v80, 0xbfb8aa3b, v76
	v_mul_f32_e32 v81, 0xbfb8aa3b, v77
	v_exp_f32_e32 v78, v78
	v_exp_f32_e32 v79, v79
	v_exp_f32_e32 v80, v80
	v_exp_f32_e32 v81, v81
	v_pk_mul_f32 v[14:15], v[14:15], v[74:75]
	v_pk_mul_f32 v[16:17], v[16:17], v[76:77]
	v_add_f32_e32 v78, 1.0, v78
	v_add_f32_e32 v79, 1.0, v79
	v_add_f32_e32 v80, 1.0, v80
	v_add_f32_e32 v81, 1.0, v81
	v_rcp_f32_e32 v78, v78
	v_rcp_f32_e32 v79, v79
	v_rcp_f32_e32 v80, v80
	v_rcp_f32_e32 v81, v81
	v_pk_mul_f32 v[14:15], v[14:15], v[78:79]
	v_pk_mul_f32 v[16:17], v[16:17], v[80:81]
	v_cvt_pk_bf16_f32 v14, v14, v15
	v_cvt_pk_bf16_f32 v15, v16, v17
	global_store_dwordx2 v[146:147], v[50:51], off
	global_store_dwordx2 v[146:147], v[54:55], off offset:256
	global_store_dwordx2 v[146:147], v[58:59], off offset:512
	global_store_dwordx2 v[146:147], v[62:63], off offset:768
	global_store_dwordx2 v[146:147], v[34:35], off offset:1024
	global_store_dwordx2 v[146:147], v[38:39], off offset:1280
	global_store_dwordx2 v[146:147], v[42:43], off offset:1536
	global_store_dwordx2 v[146:147], v[46:47], off offset:1792
	global_store_dwordx2 v[146:147], v[18:19], off offset:2048
	global_store_dwordx2 v[146:147], v[22:23], off offset:2304
	global_store_dwordx2 v[146:147], v[26:27], off offset:2560
	global_store_dwordx2 v[146:147], v[30:31], off offset:2816
	global_store_dwordx2 v[146:147], v[2:3], off offset:3072
	global_store_dwordx2 v[146:147], v[6:7], off offset:3328
	global_store_dwordx2 v[146:147], v[10:11], off offset:3584
	global_store_dwordx2 v[146:147], v[14:15], off offset:3840
	s_branch .LBB0_130

; DI unsigned pk2(float a, float b) { f32x2 v = {a, b}; bf16v2 r = __builtin_convertvector(v, bf16v2); return __builtin_bit_cast(unsigned, r); }
; DI float bf_lo(unsigned u) { return __uint_as_float(u << 16); }
; DI float bf_hi(unsigned u) { return __uint_as_float(u & 0xffff0000u); }
; DI size_t zrowU(int row0, int NT) { return ((size_t)((row0 >> 8) * NT) << 16) + (size_t)((((row0 >> 7) & 1) << 15) | (((row0 >> 5) & 1) << 14) | (((row0 >> 6) & 1) << 11)); }
; DI unsigned zlaneRC(int r5, int col) { return (unsigned)(((col >> 8) << 16) | ((r5 >> 4) << 13) | (((col >> 7) & 1) << 12) | (((col >> 5) & 3) << 9) | (((col >> 3) & 3) << 7) | ((r5 & 15) << 3) | (col & 7)); }
; DI float silu_mul(float o, float g) { return o * g * __builtin_amdgcn_rcpf(1.0f + __builtin_amdgcn_exp2f(g * -1.4426950408889634f)); }
; DI void attnA_item(bf16_t* z, const float* sinks, int hp, int qs, LAS bf16_t* vs, const LAS float* btab, int lane) {
;     ...
;     if (!metaq || c < NMETA) {
; #pragma unroll
;         for (int u = 0; u < 2; ++u) {
;             const float inv = 1.0f / l[u];
;             bf16_t* orow = z + zrowU(qrow0, 18) + zlaneRC(c, (2 * hp + u) * 64 + 4 * h);
;             const bf16_t* grow = z + zrowU(qrow0, 18) + zlaneRC(c, 2560 + (2 * hp + u) * 64 + 4 * h);
; #pragma unroll
;             for (int dt = 0; dt < 2; ++dt)
; #pragma unroll
;                 for (int g = 0; g < 4; ++g) {
;                     const int d0 = (dt << 9) | (g << 7);
;                     const u32x2 gv = *(const u32x2*)(grow + d0);
;                     u32x2 o; o.x = pk2(silu_mul(acc[u][dt][4 * g] * inv, bf_lo(gv.x)), silu_mul(acc[u][dt][4 * g + 1] * inv, bf_hi(gv.x)));
;                     o.y = pk2(silu_mul(acc[u][dt][4 * g + 2] * inv, bf_lo(gv.y)), silu_mul(acc[u][dt][4 * g + 3] * inv, bf_hi(gv.y)));
;                     *(u32x2*)(orow + d0) = o;
; DI bool attn_next(AttnQueue& q, int lane0, int& qs, int& hd) {
;     ...
;         if (lane0) n = __hip_atomic_fetch_add(q.heads + 64 * xq, 1u, __ATOMIC_RELAXED, __HIP_MEMORY_SCOPE_AGENT);
.LBB0_211:
	v_cmp_gt_u32_e32 vcc, 16, v127
	s_xor_b64 s[4:5], s[68:69], -1
	s_or_b64 s[4:5], s[4:5], vcc
	s_and_saveexec_b64 s[6:7], s[4:5]
	s_xor_b64 s[36:37], exec, s[6:7]
	s_cbranch_execz .LBB0_177
	v_div_scale_f32 v0, s[4:5], v75, v75, 1.0
	v_rcp_f32_e32 v130, v0
	v_and_b32_e32 v134, 4, v125
	v_add_u32_e32 v135, 0xa00, v125
	v_fma_f32 v148, -v0, v130, 1.0
	v_fmac_f32_e32 v130, v148, v130
	v_div_scale_f32 v148, vcc, 1.0, v75, 1.0
	v_mul_f32_e32 v149, v148, v130
	v_fma_f32 v150, -v0, v149, v148
	v_fmac_f32_e32 v149, v150, v130
	v_fma_f32 v0, -v0, v149, v148
	v_div_fmas_f32 v0, v0, v130, v149
	v_div_fixup_f32 v130, v0, v75, 1.0
	v_add_u32_e32 v0, s27, v125
	v_lshlrev_b32_e32 v136, 8, v0
	v_lshlrev_b32_e32 v0, 5, v0
	v_lshlrev_b32_e32 v137, 6, v126
	v_and_b32_e32 v136, 0xffff0000, v136
	v_and_b32_e32 v0, 0x1000, v0
	v_and_b32_e32 v146, 0x780, v137
	v_or3_b32 v0, v0, v136, v146
	v_or3_b32 v0, v0, v134, v124
	v_lshl_add_u64 v[138:139], v[0:1], 1, s[0:1]
	v_add_u32_e32 v0, s27, v135
	v_lshlrev_b32_e32 v147, 8, v0
	v_lshlrev_b32_e32 v0, 5, v0
	v_and_b32_e32 v147, 0xffff0000, v147
	v_and_b32_e32 v0, 0x1000, v0
	v_or3_b32 v0, v0, v147, v146
	v_or3_b32 v0, v0, v134, v124
	v_lshl_add_u64 v[140:141], v[0:1], 1, s[0:1]
	global_load_dwordx2 v[178:179], v[140:141], off nt
	global_load_dwordx2 v[180:181], v[140:141], off offset:256 nt
	global_load_dwordx2 v[182:183], v[140:141], off offset:512 nt
	global_load_dwordx2 v[184:185], v[140:141], off offset:768 nt
	global_load_dwordx2 v[186:187], v[140:141], off offset:1024 nt
	global_load_dwordx2 v[188:189], v[140:141], off offset:1280 nt
	global_load_dwordx2 v[190:191], v[140:141], off offset:1536 nt
	global_load_dwordx2 v[192:193], v[140:141], off offset:1792 nt
	v_div_scale_f32 v0, s[4:5], v74, v74, 1.0
	s_or_b32 s4, s27, 64
	v_rcp_f32_e32 v132, v0
	s_nop 0
	v_fma_f32 v148, -v0, v132, 1.0
	v_fmac_f32_e32 v132, v148, v132
	v_div_scale_f32 v148, vcc, 1.0, v74, 1.0
	v_mul_f32_e32 v149, v148, v132
	v_fma_f32 v150, -v0, v149, v148
	v_fmac_f32_e32 v149, v150, v132
	v_fma_f32 v0, -v0, v149, v148
	v_div_fmas_f32 v0, v0, v132, v149
	v_div_fixup_f32 v132, v0, v74, 1.0
	v_add_u32_e32 v0, s4, v125
	v_lshlrev_b32_e32 v136, 8, v0
	v_lshlrev_b32_e32 v137, 5, v0
	v_lshlrev_b32_e32 v0, 4, v0
	v_and_b32_e32 v136, 0xffff0000, v136
	v_and_b32_e32 v137, 0x1000, v137
	v_and_b32_e32 v0, 0x780, v0
	v_or3_b32 v0, v137, v136, v0
	v_or3_b32 v0, v0, v134, v124
	v_lshl_add_u64 v[142:143], v[0:1], 1, s[0:1]
	v_add_u32_e32 v0, s4, v135
	v_lshlrev_b32_e32 v136, 8, v0
	v_lshlrev_b32_e32 v147, 5, v0
	v_lshlrev_b32_e32 v0, 4, v0
	v_and_b32_e32 v136, 0xffff0000, v136
	v_and_b32_e32 v147, 0x1000, v147
	v_and_b32_e32 v0, 0x780, v0
	v_or3_b32 v0, v147, v136, v0
	v_or3_b32 v0, v0, v134, v124
	v_lshl_add_u64 v[144:145], v[0:1], 1, s[0:1]
	global_load_dwordx2 v[194:195], v[144:145], off nt
	global_load_dwordx2 v[196:197], v[144:145], off offset:256 nt
	global_load_dwordx2 v[198:199], v[144:145], off offset:512 nt
	global_load_dwordx2 v[200:201], v[144:145], off offset:768 nt
	global_load_dwordx2 v[202:203], v[144:145], off offset:1024 nt
	global_load_dwordx2 v[204:205], v[144:145], off offset:1280 nt
	global_load_dwordx2 v[206:207], v[144:145], off offset:1536 nt
	global_load_dwordx2 v[208:209], v[144:145], off offset:1792 nt
	s_add_i32 s5, s26, s33
	s_and_b32 s5, s5, 7
	s_lshl_b32 s5, s5, 8
	s_mov_b64 vcc, exec
	s_mov_b64 exec, 1
	v_mov_b32_e32 v210, s5
	v_mov_b32_e32 v211, 1
	global_atomic_add v240, v210, v211, s[34:35] sc0
	s_mov_b64 exec, vcc
	s_mov_b32 s100, 1
	v_pk_mul_f32 v[50:51], v[130:131], v[50:51] op_sel_hi:[0,1]
	v_pk_mul_f32 v[52:53], v[130:131], v[52:53] op_sel_hi:[0,1]
	v_pk_mul_f32 v[54:55], v[130:131], v[54:55] op_sel_hi:[0,1]
	v_pk_mul_f32 v[56:57], v[130:131], v[56:57] op_sel_hi:[0,1]
	v_pk_mul_f32 v[58:59], v[130:131], v[58:59] op_sel_hi:[0,1]
	v_pk_mul_f32 v[60:61], v[130:131], v[60:61] op_sel_hi:[0,1]
	v_pk_mul_f32 v[62:63], v[130:131], v[62:63] op_sel_hi:[0,1]
	v_pk_mul_f32 v[64:65], v[130:131], v[64:65] op_sel_hi:[0,1]
	v_pk_mul_f32 v[34:35], v[130:131], v[34:35] op_sel_hi:[0,1]
	v_pk_mul_f32 v[36:37], v[130:131], v[36:37] op_sel_hi:[0,1]
	v_pk_mul_f32 v[38:39], v[130:131], v[38:39] op_sel_hi:[0,1]
	v_pk_mul_f32 v[40:41], v[130:131], v[40:41] op_sel_hi:[0,1]
	v_pk_mul_f32 v[42:43], v[130:131], v[42:43] op_sel_hi:[0,1]
	v_pk_mul_f32 v[44:45], v[130:131], v[44:45] op_sel_hi:[0,1]
	v_pk_mul_f32 v[46:47], v[130:131], v[46:47] op_sel_hi:[0,1]
	v_pk_mul_f32 v[48:49], v[130:131], v[48:49] op_sel_hi:[0,1]
	v_pk_mul_f32 v[18:19], v[132:133], v[18:19] op_sel_hi:[0,1]
	v_pk_mul_f32 v[20:21], v[132:133], v[20:21] op_sel_hi:[0,1]
	v_pk_mul_f32 v[22:23], v[132:133], v[22:23] op_sel_hi:[0,1]
	v_pk_mul_f32 v[24:25], v[132:133], v[24:25] op_sel_hi:[0,1]
	v_pk_mul_f32 v[26:27], v[132:133], v[26:27] op_sel_hi:[0,1]
	v_pk_mul_f32 v[28:29], v[132:133], v[28:29] op_sel_hi:[0,1]
	v_pk_mul_f32 v[30:31], v[132:133], v[30:31] op_sel_hi:[0,1]
	v_pk_mul_f32 v[32:33], v[132:133], v[32:33] op_sel_hi:[0,1]
	v_pk_mul_f32 v[2:3], v[132:133], v[2:3] op_sel_hi:[0,1]
	v_pk_mul_f32 v[4:5], v[132:133], v[4:5] op_sel_hi:[0,1]
	v_pk_mul_f32 v[6:7], v[132:133], v[6:7] op_sel_hi:[0,1]
	v_pk_mul_f32 v[8:9], v[132:133], v[8:9] op_sel_hi:[0,1]
	v_pk_mul_f32 v[10:11], v[132:133], v[10:11] op_sel_hi:[0,1]
	v_pk_mul_f32 v[12:13], v[132:133], v[12:13] op_sel_hi:[0,1]
	v_pk_mul_f32 v[14:15], v[132:133], v[14:15] op_sel_hi:[0,1]
	v_pk_mul_f32 v[16:17], v[132:133], v[16:17] op_sel_hi:[0,1]
	s_waitcnt vmcnt(16)
; DI unsigned pk2(float a, float b) { f32x2 v = {a, b}; bf16v2 r = __builtin_convertvector(v, bf16v2); return __builtin_bit_cast(unsigned, r); }
; DI float bf_lo(unsigned u) { return __uint_as_float(u << 16); }
; DI float bf_hi(unsigned u) { return __uint_as_float(u & 0xffff0000u); }
; DI float silu_mul(float o, float g) { return o * g * __builtin_amdgcn_rcpf(1.0f + __builtin_amdgcn_exp2f(g * -1.4426950408889634f)); }
; DI void attnA_item(bf16_t* z, const float* sinks, int hp, int qs, LAS bf16_t* vs, const LAS float* btab, int lane) {
;     ...
; #pragma unroll
;             for (int dt = 0; dt < 2; ++dt)
; #pragma unroll
;                 for (int g = 0; g < 4; ++g) {
;                     const int d0 = (dt << 9) | (g << 7);
;                     const u32x2 gv = *(const u32x2*)(grow + d0);
;                     u32x2 o; o.x = pk2(silu_mul(acc[u][dt][4 * g] * inv, bf_lo(gv.x)), silu_mul(acc[u][dt][4 * g + 1] * inv, bf_hi(gv.x)));
;                     o.y = pk2(silu_mul(acc[u][dt][4 * g + 2] * inv, bf_lo(gv.y)), silu_mul(acc[u][dt][4 * g + 3] * inv, bf_hi(gv.y)));
;                     *(u32x2*)(orow + d0) = o;
	v_lshlrev_b32_e32 v210, 16, v178
	v_and_b32_e32 v211, 0xffff0000, v178
	v_lshlrev_b32_e32 v212, 16, v179
	v_and_b32_e32 v213, 0xffff0000, v179
	v_mul_f32_e32 v214, 0xbfb8aa3b, v210
	v_mul_f32_e32 v215, 0xbfb8aa3b, v211
	v_mul_f32_e32 v216, 0xbfb8aa3b, v212
	v_mul_f32_e32 v217, 0xbfb8aa3b, v213
	v_exp_f32_e32 v214, v214
	v_exp_f32_e32 v215, v215
	v_exp_f32_e32 v216, v216
	v_exp_f32_e32 v217, v217
	v_pk_mul_f32 v[50:51], v[50:51], v[210:211]
	v_pk_mul_f32 v[52:53], v[52:53], v[212:213]
	v_add_f32_e32 v214, 1.0, v214
	v_add_f32_e32 v215, 1.0, v215
	v_add_f32_e32 v216, 1.0, v216
	v_add_f32_e32 v217, 1.0, v217
	v_rcp_f32_e32 v214, v214
	v_rcp_f32_e32 v215, v215
	v_rcp_f32_e32 v216, v216
	v_rcp_f32_e32 v217, v217
	v_pk_mul_f32 v[50:51], v[50:51], v[214:215]
	v_pk_mul_f32 v[52:53], v[52:53], v[216:217]
	v_cvt_pk_bf16_f32 v50, v50, v51
	v_cvt_pk_bf16_f32 v51, v52, v53
	s_waitcnt vmcnt(15)
	v_lshlrev_b32_e32 v218, 16, v180
	v_and_b32_e32 v219, 0xffff0000, v180
	v_lshlrev_b32_e32 v220, 16, v181
	v_and_b32_e32 v221, 0xffff0000, v181
	v_mul_f32_e32 v222, 0xbfb8aa3b, v218
	v_mul_f32_e32 v223, 0xbfb8aa3b, v219
	v_mul_f32_e32 v224, 0xbfb8aa3b, v220
	v_mul_f32_e32 v225, 0xbfb8aa3b, v221
	v_exp_f32_e32 v222, v222
	v_exp_f32_e32 v223, v223
	v_exp_f32_e32 v224, v224
	v_exp_f32_e32 v225, v225
	v_pk_mul_f32 v[54:55], v[54:55], v[218:219]
	v_pk_mul_f32 v[56:57], v[56:57], v[220:221]
	v_add_f32_e32 v222, 1.0, v222
	v_add_f32_e32 v223, 1.0, v223
	v_add_f32_e32 v224, 1.0, v224
	v_add_f32_e32 v225, 1.0, v225
	v_rcp_f32_e32 v222, v222
	v_rcp_f32_e32 v223, v223
	v_rcp_f32_e32 v224, v224
	v_rcp_f32_e32 v225, v225
	v_pk_mul_f32 v[54:55], v[54:55], v[222:223]
	v_pk_mul_f32 v[56:57], v[56:57], v[224:225]
	v_cvt_pk_bf16_f32 v54, v54, v55
	v_cvt_pk_bf16_f32 v55, v56, v57
	s_waitcnt vmcnt(14)
	v_lshlrev_b32_e32 v210, 16, v182
	v_and_b32_e32 v211, 0xffff0000, v182
	v_lshlrev_b32_e32 v212, 16, v183
	v_and_b32_e32 v213, 0xffff0000, v183
	v_mul_f32_e32 v214, 0xbfb8aa3b, v210
	v_mul_f32_e32 v215, 0xbfb8aa3b, v211
	v_mul_f32_e32 v216, 0xbfb8aa3b, v212
	v_mul_f32_e32 v217, 0xbfb8aa3b, v213
	v_exp_f32_e32 v214, v214
	v_exp_f32_e32 v215, v215
	v_exp_f32_e32 v216, v216
	v_exp_f32_e32 v217, v217
	v_pk_mul_f32 v[58:59], v[58:59], v[210:211]
	v_pk_mul_f32 v[60:61], v[60:61], v[212:213]
	v_add_f32_e32 v214, 1.0, v214
	v_add_f32_e32 v215, 1.0, v215
	v_add_f32_e32 v216, 1.0, v216
	v_add_f32_e32 v217, 1.0, v217
	v_rcp_f32_e32 v214, v214
	v_rcp_f32_e32 v215, v215
	v_rcp_f32_e32 v216, v216
	v_rcp_f32_e32 v217, v217
	v_pk_mul_f32 v[58:59], v[58:59], v[214:215]
	v_pk_mul_f32 v[60:61], v[60:61], v[216:217]
	v_cvt_pk_bf16_f32 v58, v58, v59
	v_cvt_pk_bf16_f32 v59, v60, v61
	s_waitcnt vmcnt(13)
	v_lshlrev_b32_e32 v218, 16, v184
	v_and_b32_e32 v219, 0xffff0000, v184
	v_lshlrev_b32_e32 v220, 16, v185
	v_and_b32_e32 v221, 0xffff0000, v185
	v_mul_f32_e32 v222, 0xbfb8aa3b, v218
	v_mul_f32_e32 v223, 0xbfb8aa3b, v219
	v_mul_f32_e32 v224, 0xbfb8aa3b, v220
	v_mul_f32_e32 v225, 0xbfb8aa3b, v221
	v_exp_f32_e32 v222, v222
	v_exp_f32_e32 v223, v223
	v_exp_f32_e32 v224, v224
	v_exp_f32_e32 v225, v225
	v_pk_mul_f32 v[62:63], v[62:63], v[218:219]
	v_pk_mul_f32 v[64:65], v[64:65], v[220:221]
	v_add_f32_e32 v222, 1.0, v222
	v_add_f32_e32 v223, 1.0, v223
	v_add_f32_e32 v224, 1.0, v224
	v_add_f32_e32 v225, 1.0, v225
	v_rcp_f32_e32 v222, v222
	v_rcp_f32_e32 v223, v223
	v_rcp_f32_e32 v224, v224
	v_rcp_f32_e32 v225, v225
	v_pk_mul_f32 v[62:63], v[62:63], v[222:223]
	v_pk_mul_f32 v[64:65], v[64:65], v[224:225]
	v_cvt_pk_bf16_f32 v62, v62, v63
	v_cvt_pk_bf16_f32 v63, v64, v65
	s_waitcnt vmcnt(12)
	v_lshlrev_b32_e32 v210, 16, v186
	v_and_b32_e32 v211, 0xffff0000, v186
	v_lshlrev_b32_e32 v212, 16, v187
	v_and_b32_e32 v213, 0xffff0000, v187
	v_mul_f32_e32 v214, 0xbfb8aa3b, v210
	v_mul_f32_e32 v215, 0xbfb8aa3b, v211
	v_mul_f32_e32 v216, 0xbfb8aa3b, v212
	v_mul_f32_e32 v217, 0xbfb8aa3b, v213
	v_exp_f32_e32 v214, v214
	v_exp_f32_e32 v215, v215
	v_exp_f32_e32 v216, v216
	v_exp_f32_e32 v217, v217
	v_pk_mul_f32 v[34:35], v[34:35], v[210:211]
	v_pk_mul_f32 v[36:37], v[36:37], v[212:213]
	v_add_f32_e32 v214, 1.0, v214
	v_add_f32_e32 v215, 1.0, v215
	v_add_f32_e32 v216, 1.0, v216
	v_add_f32_e32 v217, 1.0, v217
	v_rcp_f32_e32 v214, v214
	v_rcp_f32_e32 v215, v215
	v_rcp_f32_e32 v216, v216
	v_rcp_f32_e32 v217, v217
	v_pk_mul_f32 v[34:35], v[34:35], v[214:215]
	v_pk_mul_f32 v[36:37], v[36:37], v[216:217]
	v_cvt_pk_bf16_f32 v34, v34, v35
	v_cvt_pk_bf16_f32 v35, v36, v37
	s_waitcnt vmcnt(11)
	v_lshlrev_b32_e32 v218, 16, v188
	v_and_b32_e32 v219, 0xffff0000, v188
	v_lshlrev_b32_e32 v220, 16, v189
	v_and_b32_e32 v221, 0xffff0000, v189
	v_mul_f32_e32 v222, 0xbfb8aa3b, v218
	v_mul_f32_e32 v223, 0xbfb8aa3b, v219
	v_mul_f32_e32 v224, 0xbfb8aa3b, v220
	v_mul_f32_e32 v225, 0xbfb8aa3b, v221
	v_exp_f32_e32 v222, v222
	v_exp_f32_e32 v223, v223
	v_exp_f32_e32 v224, v224
	v_exp_f32_e32 v225, v225
	v_pk_mul_f32 v[38:39], v[38:39], v[218:219]
	v_pk_mul_f32 v[40:41], v[40:41], v[220:221]
	v_add_f32_e32 v222, 1.0, v222
	v_add_f32_e32 v223, 1.0, v223
	v_add_f32_e32 v224, 1.0, v224
	v_add_f32_e32 v225, 1.0, v225
	v_rcp_f32_e32 v222, v222
	v_rcp_f32_e32 v223, v223
	v_rcp_f32_e32 v224, v224
	v_rcp_f32_e32 v225, v225
	v_pk_mul_f32 v[38:39], v[38:39], v[222:223]
	v_pk_mul_f32 v[40:41], v[40:41], v[224:225]
	v_cvt_pk_bf16_f32 v38, v38, v39
	v_cvt_pk_bf16_f32 v39, v40, v41
	s_waitcnt vmcnt(10)
; DI unsigned pk2(float a, float b) { f32x2 v = {a, b}; bf16v2 r = __builtin_convertvector(v, bf16v2); return __builtin_bit_cast(unsigned, r); }
; DI float bf_lo(unsigned u) { return __uint_as_float(u << 16); }
; DI float bf_hi(unsigned u) { return __uint_as_float(u & 0xffff0000u); }
; DI float silu_mul(float o, float g) { return o * g * __builtin_amdgcn_rcpf(1.0f + __builtin_amdgcn_exp2f(g * -1.4426950408889634f)); }
; DI void attnA_item(bf16_t* z, const float* sinks, int hp, int qs, LAS bf16_t* vs, const LAS float* btab, int lane) {
;     ...
; #pragma unroll
;             for (int dt = 0; dt < 2; ++dt)
; #pragma unroll
;                 for (int g = 0; g < 4; ++g) {
;                     const int d0 = (dt << 9) | (g << 7);
;                     const u32x2 gv = *(const u32x2*)(grow + d0);
;                     u32x2 o; o.x = pk2(silu_mul(acc[u][dt][4 * g] * inv, bf_lo(gv.x)), silu_mul(acc[u][dt][4 * g + 1] * inv, bf_hi(gv.x)));
;                     o.y = pk2(silu_mul(acc[u][dt][4 * g + 2] * inv, bf_lo(gv.y)), silu_mul(acc[u][dt][4 * g + 3] * inv, bf_hi(gv.y)));
;                     *(u32x2*)(orow + d0) = o;
	v_lshlrev_b32_e32 v210, 16, v190
	v_and_b32_e32 v211, 0xffff0000, v190
	v_lshlrev_b32_e32 v212, 16, v191
	v_and_b32_e32 v213, 0xffff0000, v191
	v_mul_f32_e32 v214, 0xbfb8aa3b, v210
	v_mul_f32_e32 v215, 0xbfb8aa3b, v211
	v_mul_f32_e32 v216, 0xbfb8aa3b, v212
	v_mul_f32_e32 v217, 0xbfb8aa3b, v213
	v_exp_f32_e32 v214, v214
	v_exp_f32_e32 v215, v215
	v_exp_f32_e32 v216, v216
	v_exp_f32_e32 v217, v217
	v_pk_mul_f32 v[42:43], v[42:43], v[210:211]
	v_pk_mul_f32 v[44:45], v[44:45], v[212:213]
	v_add_f32_e32 v214, 1.0, v214
	v_add_f32_e32 v215, 1.0, v215
	v_add_f32_e32 v216, 1.0, v216
	v_add_f32_e32 v217, 1.0, v217
	v_rcp_f32_e32 v214, v214
	v_rcp_f32_e32 v215, v215
	v_rcp_f32_e32 v216, v216
	v_rcp_f32_e32 v217, v217
	v_pk_mul_f32 v[42:43], v[42:43], v[214:215]
	v_pk_mul_f32 v[44:45], v[44:45], v[216:217]
	v_cvt_pk_bf16_f32 v42, v42, v43
	v_cvt_pk_bf16_f32 v43, v44, v45
	s_waitcnt vmcnt(9)
	v_lshlrev_b32_e32 v218, 16, v192
	v_and_b32_e32 v219, 0xffff0000, v192
	v_lshlrev_b32_e32 v220, 16, v193
	v_and_b32_e32 v221, 0xffff0000, v193
	v_mul_f32_e32 v222, 0xbfb8aa3b, v218
	v_mul_f32_e32 v223, 0xbfb8aa3b, v219
	v_mul_f32_e32 v224, 0xbfb8aa3b, v220
	v_mul_f32_e32 v225, 0xbfb8aa3b, v221
	v_exp_f32_e32 v222, v222
	v_exp_f32_e32 v223, v223
	v_exp_f32_e32 v224, v224
	v_exp_f32_e32 v225, v225
	v_pk_mul_f32 v[46:47], v[46:47], v[218:219]
	v_pk_mul_f32 v[48:49], v[48:49], v[220:221]
	v_add_f32_e32 v222, 1.0, v222
	v_add_f32_e32 v223, 1.0, v223
	v_add_f32_e32 v224, 1.0, v224
	v_add_f32_e32 v225, 1.0, v225
	v_rcp_f32_e32 v222, v222
	v_rcp_f32_e32 v223, v223
	v_rcp_f32_e32 v224, v224
	v_rcp_f32_e32 v225, v225
	v_pk_mul_f32 v[46:47], v[46:47], v[222:223]
	v_pk_mul_f32 v[48:49], v[48:49], v[224:225]
	v_cvt_pk_bf16_f32 v46, v46, v47
	v_cvt_pk_bf16_f32 v47, v48, v49
	s_waitcnt vmcnt(8)
	v_lshlrev_b32_e32 v210, 16, v194
	v_and_b32_e32 v211, 0xffff0000, v194
	v_lshlrev_b32_e32 v212, 16, v195
	v_and_b32_e32 v213, 0xffff0000, v195
	v_mul_f32_e32 v214, 0xbfb8aa3b, v210
	v_mul_f32_e32 v215, 0xbfb8aa3b, v211
	v_mul_f32_e32 v216, 0xbfb8aa3b, v212
	v_mul_f32_e32 v217, 0xbfb8aa3b, v213
	v_exp_f32_e32 v214, v214
	v_exp_f32_e32 v215, v215
	v_exp_f32_e32 v216, v216
	v_exp_f32_e32 v217, v217
	v_pk_mul_f32 v[18:19], v[18:19], v[210:211]
	v_pk_mul_f32 v[20:21], v[20:21], v[212:213]
	v_add_f32_e32 v214, 1.0, v214
	v_add_f32_e32 v215, 1.0, v215
	v_add_f32_e32 v216, 1.0, v216
	v_add_f32_e32 v217, 1.0, v217
	v_rcp_f32_e32 v214, v214
	v_rcp_f32_e32 v215, v215
	v_rcp_f32_e32 v216, v216
	v_rcp_f32_e32 v217, v217
	v_pk_mul_f32 v[18:19], v[18:19], v[214:215]
	v_pk_mul_f32 v[20:21], v[20:21], v[216:217]
	v_cvt_pk_bf16_f32 v18, v18, v19
	v_cvt_pk_bf16_f32 v19, v20, v21
	s_waitcnt vmcnt(7)
	v_lshlrev_b32_e32 v218, 16, v196
	v_and_b32_e32 v219, 0xffff0000, v196
	v_lshlrev_b32_e32 v220, 16, v197
	v_and_b32_e32 v221, 0xffff0000, v197
	v_mul_f32_e32 v222, 0xbfb8aa3b, v218
	v_mul_f32_e32 v223, 0xbfb8aa3b, v219
	v_mul_f32_e32 v224, 0xbfb8aa3b, v220
	v_mul_f32_e32 v225, 0xbfb8aa3b, v221
	v_exp_f32_e32 v222, v222
	v_exp_f32_e32 v223, v223
	v_exp_f32_e32 v224, v224
	v_exp_f32_e32 v225, v225
	v_pk_mul_f32 v[22:23], v[22:23], v[218:219]
	v_pk_mul_f32 v[24:25], v[24:25], v[220:221]
	v_add_f32_e32 v222, 1.0, v222
	v_add_f32_e32 v223, 1.0, v223
	v_add_f32_e32 v224, 1.0, v224
	v_add_f32_e32 v225, 1.0, v225
	v_rcp_f32_e32 v222, v222
	v_rcp_f32_e32 v223, v223
	v_rcp_f32_e32 v224, v224
	v_rcp_f32_e32 v225, v225
	v_pk_mul_f32 v[22:23], v[22:23], v[222:223]
	v_pk_mul_f32 v[24:25], v[24:25], v[224:225]
	v_cvt_pk_bf16_f32 v22, v22, v23
	v_cvt_pk_bf16_f32 v23, v24, v25
	s_waitcnt vmcnt(6)
	v_lshlrev_b32_e32 v210, 16, v198
	v_and_b32_e32 v211, 0xffff0000, v198
	v_lshlrev_b32_e32 v212, 16, v199
	v_and_b32_e32 v213, 0xffff0000, v199
	v_mul_f32_e32 v214, 0xbfb8aa3b, v210
	v_mul_f32_e32 v215, 0xbfb8aa3b, v211
	v_mul_f32_e32 v216, 0xbfb8aa3b, v212
	v_mul_f32_e32 v217, 0xbfb8aa3b, v213
	v_exp_f32_e32 v214, v214
	v_exp_f32_e32 v215, v215
	v_exp_f32_e32 v216, v216
	v_exp_f32_e32 v217, v217
	v_pk_mul_f32 v[26:27], v[26:27], v[210:211]
	v_pk_mul_f32 v[28:29], v[28:29], v[212:213]
	v_add_f32_e32 v214, 1.0, v214
	v_add_f32_e32 v215, 1.0, v215
	v_add_f32_e32 v216, 1.0, v216
	v_add_f32_e32 v217, 1.0, v217
	v_rcp_f32_e32 v214, v214
	v_rcp_f32_e32 v215, v215
	v_rcp_f32_e32 v216, v216
	v_rcp_f32_e32 v217, v217
	v_pk_mul_f32 v[26:27], v[26:27], v[214:215]
	v_pk_mul_f32 v[28:29], v[28:29], v[216:217]
	v_cvt_pk_bf16_f32 v26, v26, v27
	v_cvt_pk_bf16_f32 v27, v28, v29
	s_waitcnt vmcnt(5)
; DI unsigned pk2(float a, float b) { f32x2 v = {a, b}; bf16v2 r = __builtin_convertvector(v, bf16v2); return __builtin_bit_cast(unsigned, r); }
; DI float bf_lo(unsigned u) { return __uint_as_float(u << 16); }
; DI float bf_hi(unsigned u) { return __uint_as_float(u & 0xffff0000u); }
; DI float silu_mul(float o, float g) { return o * g * __builtin_amdgcn_rcpf(1.0f + __builtin_amdgcn_exp2f(g * -1.4426950408889634f)); }
; DI void attnA_item(bf16_t* z, const float* sinks, int hp, int qs, LAS bf16_t* vs, const LAS float* btab, int lane) {
;     ...
; #pragma unroll
;             for (int dt = 0; dt < 2; ++dt)
; #pragma unroll
;                 for (int g = 0; g < 4; ++g) {
;                     const int d0 = (dt << 9) | (g << 7);
;                     const u32x2 gv = *(const u32x2*)(grow + d0);
;                     u32x2 o; o.x = pk2(silu_mul(acc[u][dt][4 * g] * inv, bf_lo(gv.x)), silu_mul(acc[u][dt][4 * g + 1] * inv, bf_hi(gv.x)));
;                     o.y = pk2(silu_mul(acc[u][dt][4 * g + 2] * inv, bf_lo(gv.y)), silu_mul(acc[u][dt][4 * g + 3] * inv, bf_hi(gv.y)));
;                     *(u32x2*)(orow + d0) = o;
	v_lshlrev_b32_e32 v218, 16, v200
	v_and_b32_e32 v219, 0xffff0000, v200
	v_lshlrev_b32_e32 v220, 16, v201
	v_and_b32_e32 v221, 0xffff0000, v201
	v_mul_f32_e32 v222, 0xbfb8aa3b, v218
	v_mul_f32_e32 v223, 0xbfb8aa3b, v219
	v_mul_f32_e32 v224, 0xbfb8aa3b, v220
	v_mul_f32_e32 v225, 0xbfb8aa3b, v221
	v_exp_f32_e32 v222, v222
	v_exp_f32_e32 v223, v223
	v_exp_f32_e32 v224, v224
	v_exp_f32_e32 v225, v225
	v_pk_mul_f32 v[30:31], v[30:31], v[218:219]
	v_pk_mul_f32 v[32:33], v[32:33], v[220:221]
	v_add_f32_e32 v222, 1.0, v222
	v_add_f32_e32 v223, 1.0, v223
	v_add_f32_e32 v224, 1.0, v224
	v_add_f32_e32 v225, 1.0, v225
	v_rcp_f32_e32 v222, v222
	v_rcp_f32_e32 v223, v223
	v_rcp_f32_e32 v224, v224
	v_rcp_f32_e32 v225, v225
	v_pk_mul_f32 v[30:31], v[30:31], v[222:223]
	v_pk_mul_f32 v[32:33], v[32:33], v[224:225]
	v_cvt_pk_bf16_f32 v30, v30, v31
	v_cvt_pk_bf16_f32 v31, v32, v33
	s_waitcnt vmcnt(4)
	v_lshlrev_b32_e32 v210, 16, v202
	v_and_b32_e32 v211, 0xffff0000, v202
	v_lshlrev_b32_e32 v212, 16, v203
	v_and_b32_e32 v213, 0xffff0000, v203
	v_mul_f32_e32 v214, 0xbfb8aa3b, v210
	v_mul_f32_e32 v215, 0xbfb8aa3b, v211
	v_mul_f32_e32 v216, 0xbfb8aa3b, v212
	v_mul_f32_e32 v217, 0xbfb8aa3b, v213
	v_exp_f32_e32 v214, v214
	v_exp_f32_e32 v215, v215
	v_exp_f32_e32 v216, v216
	v_exp_f32_e32 v217, v217
	v_pk_mul_f32 v[2:3], v[2:3], v[210:211]
	v_pk_mul_f32 v[4:5], v[4:5], v[212:213]
	v_add_f32_e32 v214, 1.0, v214
	v_add_f32_e32 v215, 1.0, v215
	v_add_f32_e32 v216, 1.0, v216
	v_add_f32_e32 v217, 1.0, v217
	v_rcp_f32_e32 v214, v214
	v_rcp_f32_e32 v215, v215
	v_rcp_f32_e32 v216, v216
	v_rcp_f32_e32 v217, v217
	v_pk_mul_f32 v[2:3], v[2:3], v[214:215]
	v_pk_mul_f32 v[4:5], v[4:5], v[216:217]
	v_cvt_pk_bf16_f32 v2, v2, v3
	v_cvt_pk_bf16_f32 v3, v4, v5
	s_waitcnt vmcnt(3)
	v_lshlrev_b32_e32 v218, 16, v204
	v_and_b32_e32 v219, 0xffff0000, v204
	v_lshlrev_b32_e32 v220, 16, v205
	v_and_b32_e32 v221, 0xffff0000, v205
	v_mul_f32_e32 v222, 0xbfb8aa3b, v218
	v_mul_f32_e32 v223, 0xbfb8aa3b, v219
	v_mul_f32_e32 v224, 0xbfb8aa3b, v220
	v_mul_f32_e32 v225, 0xbfb8aa3b, v221
	v_exp_f32_e32 v222, v222
	v_exp_f32_e32 v223, v223
	v_exp_f32_e32 v224, v224
	v_exp_f32_e32 v225, v225
	v_pk_mul_f32 v[6:7], v[6:7], v[218:219]
	v_pk_mul_f32 v[8:9], v[8:9], v[220:221]
	v_add_f32_e32 v222, 1.0, v222
	v_add_f32_e32 v223, 1.0, v223
	v_add_f32_e32 v224, 1.0, v224
	v_add_f32_e32 v225, 1.0, v225
	v_rcp_f32_e32 v222, v222
	v_rcp_f32_e32 v223, v223
	v_rcp_f32_e32 v224, v224
	v_rcp_f32_e32 v225, v225
	v_pk_mul_f32 v[6:7], v[6:7], v[222:223]
	v_pk_mul_f32 v[8:9], v[8:9], v[224:225]
	v_cvt_pk_bf16_f32 v6, v6, v7
	v_cvt_pk_bf16_f32 v7, v8, v9
	s_waitcnt vmcnt(2)
	v_lshlrev_b32_e32 v210, 16, v206
	v_and_b32_e32 v211, 0xffff0000, v206
	v_lshlrev_b32_e32 v212, 16, v207
	v_and_b32_e32 v213, 0xffff0000, v207
	v_mul_f32_e32 v214, 0xbfb8aa3b, v210
	v_mul_f32_e32 v215, 0xbfb8aa3b, v211
	v_mul_f32_e32 v216, 0xbfb8aa3b, v212
	v_mul_f32_e32 v217, 0xbfb8aa3b, v213
	v_exp_f32_e32 v214, v214
	v_exp_f32_e32 v215, v215
	v_exp_f32_e32 v216, v216
	v_exp_f32_e32 v217, v217
	v_pk_mul_f32 v[10:11], v[10:11], v[210:211]
	v_pk_mul_f32 v[12:13], v[12:13], v[212:213]
	v_add_f32_e32 v214, 1.0, v214
	v_add_f32_e32 v215, 1.0, v215
	v_add_f32_e32 v216, 1.0, v216
	v_add_f32_e32 v217, 1.0, v217
	v_rcp_f32_e32 v214, v214
	v_rcp_f32_e32 v215, v215
	v_rcp_f32_e32 v216, v216
	v_rcp_f32_e32 v217, v217
	v_pk_mul_f32 v[10:11], v[10:11], v[214:215]
	v_pk_mul_f32 v[12:13], v[12:13], v[216:217]
	v_cvt_pk_bf16_f32 v10, v10, v11
	v_cvt_pk_bf16_f32 v11, v12, v13
	s_waitcnt vmcnt(1)
	v_lshlrev_b32_e32 v218, 16, v208
	v_and_b32_e32 v219, 0xffff0000, v208
	v_lshlrev_b32_e32 v220, 16, v209
	v_and_b32_e32 v221, 0xffff0000, v209
	v_mul_f32_e32 v222, 0xbfb8aa3b, v218
	v_mul_f32_e32 v223, 0xbfb8aa3b, v219
	v_mul_f32_e32 v224, 0xbfb8aa3b, v220
	v_mul_f32_e32 v225, 0xbfb8aa3b, v221
	v_exp_f32_e32 v222, v222
	v_exp_f32_e32 v223, v223
	v_exp_f32_e32 v224, v224
	v_exp_f32_e32 v225, v225
	v_pk_mul_f32 v[14:15], v[14:15], v[218:219]
	v_pk_mul_f32 v[16:17], v[16:17], v[220:221]
	v_add_f32_e32 v222, 1.0, v222
	v_add_f32_e32 v223, 1.0, v223
	v_add_f32_e32 v224, 1.0, v224
	v_add_f32_e32 v225, 1.0, v225
	v_rcp_f32_e32 v222, v222
	v_rcp_f32_e32 v223, v223
	v_rcp_f32_e32 v224, v224
	v_rcp_f32_e32 v225, v225
	v_pk_mul_f32 v[14:15], v[14:15], v[222:223]
	v_pk_mul_f32 v[16:17], v[16:17], v[224:225]
	v_cvt_pk_bf16_f32 v14, v14, v15
	v_cvt_pk_bf16_f32 v15, v16, v17
	global_store_dwordx2 v[138:139], v[50:51], off
	global_store_dwordx2 v[138:139], v[54:55], off offset:256
	global_store_dwordx2 v[138:139], v[58:59], off offset:512
	global_store_dwordx2 v[138:139], v[62:63], off offset:768
	global_store_dwordx2 v[138:139], v[34:35], off offset:1024
	global_store_dwordx2 v[138:139], v[38:39], off offset:1280
	global_store_dwordx2 v[138:139], v[42:43], off offset:1536
	global_store_dwordx2 v[138:139], v[46:47], off offset:1792
	global_store_dwordx2 v[142:143], v[18:19], off
	global_store_dwordx2 v[142:143], v[22:23], off offset:256
	global_store_dwordx2 v[142:143], v[26:27], off offset:512
	global_store_dwordx2 v[142:143], v[30:31], off offset:768
	global_store_dwordx2 v[142:143], v[2:3], off offset:1024
	global_store_dwordx2 v[142:143], v[6:7], off offset:1280
	global_store_dwordx2 v[142:143], v[10:11], off offset:1536
	global_store_dwordx2 v[142:143], v[14:15], off offset:1792
	s_branch .LBB0_177
